# v92 plus the latency-only edits kept out so far: first hgrn_pass_c MFMA stage prefetched, cumsum reads batched, gate-LoRA operand loads batched
# speedup vs baseline: 1.0043x; 1.0043x over previous
.LBB0_856:
	s_or_b64 exec, exec, s[0:1]
	v_bfe_u32 v108, v196, 6, 1
	v_ashrrev_i32_e32 v110, 7, v196
	s_mov_b32 s0, 0x13000
	v_mad_u32_u24 v94, v108, s0, 0
	v_lshlrev_b32_e32 v95, 12, v110
	v_lshlrev_b32_e32 v109, 2, v199
	s_waitcnt lgkmcnt(0)
	s_barrier
	s_ashr_i32 s80, s72, 3
	v_readlane_b32 s81, v255, 20
	v_lshrrev_b32_e32 v228, 8, v177
	s_ashr_i32 s82, s80, s81
	s_and_b32 s83, s80, s62
	s_lshl_b32 s82, s82, 3
	s_or_b32 s82, s82, s74
	s_lshl_b32 s82, s82, 1
	v_readfirstlane_b32 s84, v228
	v_readlane_b32 s86, v253, 7
	v_readlane_b32 s87, v253, 8
	v_and_b32_e32 v228, 31, v177
	v_bfe_u32 v229, v177, 6, 2
	s_add_u32 s82, s82, s84
	s_lshl_b32 s82, s82, s81
	s_sub_u32 s85, s62, s83
	s_cmp_eq_u32 s84, 0
	s_cselect_b32 s83, s83, s85
	s_add_u32 s82, s82, s83
	s_lshr_b32 s85, s82, 17
	s_lshl_b32 s84, s82, 15
	s_add_u32 s86, s86, s84
	s_addc_u32 s87, s87, s85
	v_lshl_or_b32 v228, v229, 5, v228
	v_lshlrev_b32_e32 v228, 7, v228
	global_load_dword v229, v228, s[86:87]
	v_add3_u32 v111, v94, v95, v109
	ds_read2st64_b32 v[94:95], v111 offset0:192 offset1:193
	ds_read2st64_b32 v[96:97], v111 offset0:194 offset1:195
	ds_read2st64_b32 v[236:237], v111 offset0:196 offset1:197
	ds_read2st64_b32 v[238:239], v111 offset0:198 offset1:199
	ds_read2st64_b32 v[240:241], v111 offset0:200 offset1:201
	ds_read2st64_b32 v[242:243], v111 offset0:202 offset1:203
	ds_read2st64_b32 v[244:245], v111 offset0:204 offset1:205
	ds_read2st64_b32 v[246:247], v111 offset0:206 offset1:207
	v_lshlrev_b32_e32 v144, 10, v108
	v_readlane_b32 s0, v254, 53
	v_ashrrev_i32_e32 v0, 8, v196
	s_waitcnt lgkmcnt(7)
	v_add_f32_e32 v95, v94, v95
	s_waitcnt lgkmcnt(6)
	v_add_f32_e32 v112, v96, v95
	v_add_f32_e32 v113, v97, v112
	v_cmp_eq_u32_e32 vcc, 1, v0
	v_lshlrev_b32_e32 v166, 2, v192
	s_waitcnt lgkmcnt(5)
	v_add_f32_e32 v114, v236, v113
	v_add_f32_e32 v115, v237, v114
	s_waitcnt lgkmcnt(4)
	v_add_f32_e32 v116, v238, v115
	v_add_f32_e32 v117, v239, v116
	s_waitcnt lgkmcnt(3)
	v_add_f32_e32 v118, v240, v117
	v_add_f32_e32 v119, v241, v118
	s_waitcnt lgkmcnt(2)
	v_add_f32_e32 v120, v242, v119
	v_add_f32_e32 v121, v243, v120
	s_waitcnt lgkmcnt(1)
	v_add_f32_e32 v122, v244, v121
	v_add_f32_e32 v123, v245, v122
	s_waitcnt lgkmcnt(0)
	v_add_f32_e32 v142, v246, v123
	v_add_f32_e32 v143, v247, v142
	v_lshlrev_b32_e32 v96, 8, v110
	v_add_u32_e32 v97, s0, v144
	v_add3_u32 v96, v97, v96, v109
	ds_write_b32 v96, v143
	s_and_saveexec_b64 s[0:1], vcc
	s_cbranch_execz .LBB0_865
	v_lshlrev_b32_e32 v96, 10, v194
	v_lshl_or_b32 v96, v198, 12, v96
	s_add_i32 s4, 0, 0x11000
	v_add3_u32 v145, s4, v166, v96
	ds_read2_b32 v[98:99], v145 offset1:16
	ds_read2_b32 v[104:105], v145 offset0:64 offset1:80
	ds_read2_b32 v[146:147], v145 offset0:32 offset1:48
	ds_read2_b32 v[100:101], v145 offset0:128 offset1:144
	ds_read2_b32 v[96:97], v145 offset0:192 offset1:208
	s_waitcnt lgkmcnt(4)
	v_fma_f32 v148, v68, v98, 0
	v_fmac_f32_e32 v148, v64, v99
	s_waitcnt lgkmcnt(2)
	v_fmac_f32_e32 v148, v72, v146
	v_and_b32_e32 v146, 64, v179
	ds_read2_b32 v[106:107], v145 offset0:96 offset1:112
	ds_read2_b32 v[102:103], v145 offset0:160 offset1:176
	ds_read2_b32 v[98:99], v145 offset0:224 offset1:240
	v_xor_b32_e32 v145, 1, v179
	v_add_u32_e32 v149, 64, v146
	v_cmp_lt_i32_e32 vcc, v145, v149
	v_fmac_f32_e32 v148, v76, v147
	v_xor_b32_e32 v146, 2, v179
	v_cndmask_b32_e32 v145, v179, v145, vcc
	v_lshlrev_b32_e32 v145, 2, v145
	s_nop 1
	v_mov_b32_dpp v147, v148 quad_perm:[1,0,3,2] row_mask:0xf bank_mask:0xf
	v_cmp_lt_i32_e32 vcc, v146, v149
	v_xor_b32_e32 v153, 8, v179
	v_readlane_b32 s4, v254, 59
	v_cndmask_b32_e32 v146, v179, v146, vcc
	v_lshlrev_b32_e32 v146, 2, v146
	s_waitcnt lgkmcnt(0)
	v_add_f32_e32 v148, v148, v147
	s_nop 1
	v_mov_b32_dpp v152, v148 quad_perm:[2,3,0,1] row_mask:0xf bank_mask:0xf
	v_xor_b32_e32 v147, 4, v179
	v_cmp_lt_i32_e32 vcc, v147, v149
	s_waitcnt lgkmcnt(0)
	v_add_f32_e32 v148, v148, v152
	v_cndmask_b32_e32 v147, v179, v147, vcc
	v_lshlrev_b32_e32 v147, 2, v147
	s_nop 1
	v_mov_b32_dpp v152, v148 row_shl:4 row_mask:0xf bank_mask:0x5
	s_nop 1
	v_mov_b32_dpp v152, v148 row_shr:4 row_mask:0xf bank_mask:0xa
	v_cmp_lt_i32_e32 vcc, v153, v149
	s_waitcnt lgkmcnt(0)
	v_add_f32_e32 v152, v148, v152
	v_cndmask_b32_e32 v149, v179, v153, vcc
	v_lshlrev_b32_e32 v149, 2, v149
	s_nop 1
	v_mov_b32_dpp v153, v152 row_shl:8 row_mask:0xf bank_mask:0x3
	s_nop 1
	v_mov_b32_dpp v153, v152 row_shr:8 row_mask:0xf bank_mask:0xc
	v_lshl_add_u32 v148, v198, 6, s4
	v_cmp_eq_u32_e32 vcc, 0, v192
	v_add_u32_e32 v148, v148, v200
	s_and_saveexec_b64 s[24:25], vcc
	s_cbranch_execz .LBB0_859
	s_waitcnt lgkmcnt(0)
	v_add_f32_e32 v152, v152, v153
	ds_write_b32 v148, v152

.LBB0_1121:
	s_waitcnt lgkmcnt(0)
	s_barrier
	s_mov_b64 s[24:25], -1
	s_and_b64 vcc, exec, s[88:89]
	ds_read_b128 v[188:191], v34 offset:17408
	ds_read_b128 v[192:195], v34 offset:17472
	ds_read_b128 v[196:199], v34 offset:17536
	ds_read_b128 v[200:203], v34 offset:17600
	ds_read_b128 v[204:207], v145 offset:34816
	ds_read_b128 v[208:211], v145 offset:34880
	ds_read_b128 v[212:215], v145 offset:34944
	ds_read_b128 v[216:219], v145 offset:35008
	ds_read_b128 v[220:223], v145 offset:39168
	ds_read_b128 v[224:227], v145 offset:39232
	ds_read_b128 v[228:231], v145 offset:39296
	ds_read_b128 v[232:235], v145 offset:39360
	s_waitcnt lgkmcnt(4)
	v_mfma_f32_16x16x32_bf16 v[26:29], v[188:191], v[204:207], 0
	v_mfma_f32_16x16x32_bf16 v[26:29], v[192:195], v[208:211], v[26:29]
	v_mfma_f32_16x16x32_bf16 v[26:29], v[196:199], v[212:215], v[26:29]
	v_mfma_f32_16x16x32_bf16 v[26:29], v[200:203], v[216:219], v[26:29]
	s_nop 7
	v_cndmask_b32_e64 v0, v26, 0, s[70:71]
	v_cvt_pk_bf16_f32 v0, v0, v0
	ds_write_b16 v146, v0
	v_cndmask_b32_e64 v0, v27, 0, s[72:73]
	v_cvt_pk_bf16_f32 v0, v0, v0
	ds_write_b16 v146, v0 offset:144
	v_cndmask_b32_e64 v0, v28, 0, s[74:75]
	v_cvt_pk_bf16_f32 v0, v0, v0
	ds_write_b16 v146, v0 offset:288
	v_cndmask_b32_e64 v0, v29, 0, s[76:77]
	v_cvt_pk_bf16_f32 v0, v0, v0
	ds_write_b16 v146, v0 offset:432
	s_waitcnt lgkmcnt(0)
	v_mfma_f32_16x16x32_bf16 v[26:29], v[188:191], v[220:223], 0
	v_mfma_f32_16x16x32_bf16 v[26:29], v[192:195], v[224:227], v[26:29]
	v_mfma_f32_16x16x32_bf16 v[26:29], v[196:199], v[228:231], v[26:29]
	v_mfma_f32_16x16x32_bf16 v[26:29], v[200:203], v[232:235], v[26:29]
	s_nop 7
	v_cndmask_b32_e64 v0, v26, 0, s[78:79]
	v_cvt_pk_bf16_f32 v0, v0, v0
	ds_write_b16 v147, v0
	v_cndmask_b32_e64 v0, v27, 0, s[80:81]
	v_cvt_pk_bf16_f32 v0, v0, v0
	ds_write_b16 v147, v0 offset:144
	v_cndmask_b32_e64 v0, v28, 0, s[82:83]
	v_cvt_pk_bf16_f32 v0, v0, v0
	ds_write_b16 v147, v0 offset:288
	v_cndmask_b32_e64 v0, v29, 0, s[84:85]
	v_cvt_pk_bf16_f32 v0, v0, v0
	ds_write_b16 v147, v0 offset:432
	s_waitcnt lgkmcnt(0)
	s_barrier
	ds_read_b128 v[188:191], v34
	ds_read_b128 v[192:195], v34 offset:64
	ds_read_b128 v[196:199], v34 offset:128
	ds_read_b128 v[200:203], v34 offset:192
	ds_read_b128 v[204:207], v35
	ds_read_b128 v[208:211], v35 offset:64
	ds_read_b128 v[212:215], v148
	ds_read_b128 v[216:219], v148 offset:64
	ds_read_b128 v[220:223], v148 offset:128
	ds_read_b128 v[224:227], v148 offset:192
	ds_read_b128 v[244:247], v149 offset:52224
	ds_read_b128 v[248:251], v149 offset:52288
	s_waitcnt lgkmcnt(2)
	v_mfma_f32_16x16x32_bf16 v[26:29], v[188:191], v[212:215], 0
	v_mfma_f32_16x16x32_bf16 v[26:29], v[192:195], v[216:219], v[26:29]
	v_mfma_f32_16x16x32_bf16 v[26:29], v[196:199], v[220:223], v[26:29]
	v_mfma_f32_16x16x32_bf16 v[26:29], v[200:203], v[224:227], v[26:29]
	ds_read_b128 v[228:231], v148 offset:4352
	ds_read_b128 v[232:235], v148 offset:4416
	ds_read_b128 v[236:239], v148 offset:4480
	ds_read_b128 v[240:243], v148 offset:4544
	s_waitcnt lgkmcnt(4)
	v_mfma_f32_16x16x32_bf16 v[26:29], v[204:207], v[244:247], v[26:29]
	v_mfma_f32_16x16x32_bf16 v[26:29], v[208:211], v[248:251], v[26:29]
	s_cbranch_vccnz .LBB0_1161
	s_andn2_b64 vcc, exec, s[24:25]
	v_add_u32_e32 v0, v111, v113
	s_cbranch_vccz .LBB0_1162
